# P2: pooling preamble (up to 15 previous rows) and kv-latent normalisation pass loads batched into one round trip
# speedup vs baseline: 1.0102x; 1.0102x over previous
.LBB0_339:
	s_lshl_b32 s10, s35, 5
	s_ashr_i32 s11, s10, 31
	s_and_b32 s16, s10, 0xfe0
	s_lshl_b64 s[10:11], s[10:11], 10
	s_cmp_eq_u32 s16, 0
	s_cselect_b64 s[52:53], -1, 0
	v_lshl_add_u64 v[0:1], v[32:33], 0, s[10:11]
	s_and_b64 vcc, exec, s[52:53]
	v_mov_b32_e32 v10, 0
	v_mov_b32_e32 v11, 0
	v_mov_b32_e32 v2, 0
	v_mov_b32_e32 v3, 0
	v_mov_b32_e32 v4, 0
	v_mov_b32_e32 v5, 0
	v_mov_b32_e32 v6, 0
	v_mov_b32_e32 v7, 0
	v_mov_b32_e32 v8, 0
	v_mov_b32_e32 v9, 0
	s_cbranch_vccnz .Lpool_zero
	v_add_co_u32_e32 v124, vcc, 0xfffff000, v0
	s_nop 1
	v_addc_co_u32_e32 v125, vcc, -1, v1, vcc
	v_add_co_u32_e32 v126, vcc, 0xffffe000, v0
	s_nop 1
	v_addc_co_u32_e32 v127, vcc, -1, v1, vcc
	v_add_co_u32_e32 v128, vcc, 0xffffd000, v0
	s_nop 1
	v_addc_co_u32_e32 v129, vcc, -1, v1, vcc
	global_load_dwordx4 v[64:67], v[0:1], off offset:-1024
	global_load_dwordx4 v[68:71], v[0:1], off offset:-2048
	global_load_dwordx4 v[72:75], v[0:1], off offset:-3072
	global_load_dwordx4 v[76:79], v[0:1], off offset:-4096
	global_load_dwordx4 v[80:83], v[124:125], off offset:-1024
	global_load_dwordx4 v[84:87], v[124:125], off offset:-2048
	global_load_dwordx4 v[88:91], v[124:125], off offset:-3072
	global_load_dwordx4 v[92:95], v[124:125], off offset:-4096
	global_load_dwordx4 v[96:99], v[126:127], off offset:-1024
	global_load_dwordx4 v[100:103], v[126:127], off offset:-2048
	global_load_dwordx4 v[104:107], v[126:127], off offset:-3072
	global_load_dwordx4 v[108:111], v[126:127], off offset:-4096
	global_load_dwordx4 v[112:115], v[128:129], off offset:-1024
	global_load_dwordx4 v[116:119], v[128:129], off offset:-2048
	global_load_dwordx4 v[120:123], v[128:129], off offset:-3072
	v_mov_b32_e32 v40, 0
	v_mov_b32_e32 v44, 0
	v_mov_b32_e32 v41, 0
	v_mov_b32_e32 v45, 0
	v_mov_b32_e32 v42, 0
	v_mov_b32_e32 v46, 0
	v_mov_b32_e32 v43, 0
	v_mov_b32_e32 v47, 0
	s_waitcnt vmcnt(0)
	v_lshlrev_b32_e32 v130, 16, v64
	v_and_b32_e32 v131, 0xffff0000, v64
	v_lshlrev_b32_e32 v132, 16, v65
	v_and_b32_e32 v133, 0xffff0000, v65
	v_lshlrev_b32_e32 v134, 16, v66
	v_and_b32_e32 v135, 0xffff0000, v66
	v_lshlrev_b32_e32 v136, 16, v67
	v_and_b32_e32 v137, 0xffff0000, v67
	v_add_f32_e32 v40, v40, v130
	v_add_f32_e32 v44, v44, v131
	v_add_f32_e32 v41, v41, v132
	v_add_f32_e32 v45, v45, v133
	v_add_f32_e32 v42, v42, v134
	v_add_f32_e32 v46, v46, v135
	v_add_f32_e32 v43, v43, v136
	v_add_f32_e32 v47, v47, v137
	s_andn2_b64 exec, exec, s[0:1]
	v_lshlrev_b32_e32 v130, 16, v68
	v_and_b32_e32 v131, 0xffff0000, v68
	v_lshlrev_b32_e32 v132, 16, v69
	v_and_b32_e32 v133, 0xffff0000, v69
	v_lshlrev_b32_e32 v134, 16, v70
	v_and_b32_e32 v135, 0xffff0000, v70
	v_lshlrev_b32_e32 v136, 16, v71
	v_and_b32_e32 v137, 0xffff0000, v71
	v_add_f32_e32 v40, v40, v130
	v_add_f32_e32 v44, v44, v131
	v_add_f32_e32 v41, v41, v132
	v_add_f32_e32 v45, v45, v133
	v_add_f32_e32 v42, v42, v134
	v_add_f32_e32 v46, v46, v135
	v_add_f32_e32 v43, v43, v136
	v_add_f32_e32 v47, v47, v137
	v_lshlrev_b32_e32 v130, 16, v72
	v_and_b32_e32 v131, 0xffff0000, v72
	v_lshlrev_b32_e32 v132, 16, v73
	v_and_b32_e32 v133, 0xffff0000, v73
	v_lshlrev_b32_e32 v134, 16, v74
	v_and_b32_e32 v135, 0xffff0000, v74
	v_lshlrev_b32_e32 v136, 16, v75
	v_and_b32_e32 v137, 0xffff0000, v75
	v_add_f32_e32 v40, v40, v130
	v_add_f32_e32 v44, v44, v131
	v_add_f32_e32 v41, v41, v132
	v_add_f32_e32 v45, v45, v133
	v_add_f32_e32 v42, v42, v134
	v_add_f32_e32 v46, v46, v135
	v_add_f32_e32 v43, v43, v136
	v_add_f32_e32 v47, v47, v137
	s_andn2_b64 exec, exec, s[6:7]
	v_lshlrev_b32_e32 v130, 16, v76
	v_and_b32_e32 v131, 0xffff0000, v76
	v_lshlrev_b32_e32 v132, 16, v77
	v_and_b32_e32 v133, 0xffff0000, v77
	v_lshlrev_b32_e32 v134, 16, v78
	v_and_b32_e32 v135, 0xffff0000, v78
	v_lshlrev_b32_e32 v136, 16, v79
	v_and_b32_e32 v137, 0xffff0000, v79
	v_add_f32_e32 v40, v40, v130
	v_add_f32_e32 v44, v44, v131
	v_add_f32_e32 v41, v41, v132
	v_add_f32_e32 v45, v45, v133
	v_add_f32_e32 v42, v42, v134
	v_add_f32_e32 v46, v46, v135
	v_add_f32_e32 v43, v43, v136
	v_add_f32_e32 v47, v47, v137
	v_lshlrev_b32_e32 v130, 16, v80
	v_and_b32_e32 v131, 0xffff0000, v80
	v_lshlrev_b32_e32 v132, 16, v81
	v_and_b32_e32 v133, 0xffff0000, v81
	v_lshlrev_b32_e32 v134, 16, v82
	v_and_b32_e32 v135, 0xffff0000, v82
	v_lshlrev_b32_e32 v136, 16, v83
	v_and_b32_e32 v137, 0xffff0000, v83
	v_add_f32_e32 v40, v40, v130
	v_add_f32_e32 v44, v44, v131
	v_add_f32_e32 v41, v41, v132
	v_add_f32_e32 v45, v45, v133
	v_add_f32_e32 v42, v42, v134
	v_add_f32_e32 v46, v46, v135
	v_add_f32_e32 v43, v43, v136
	v_add_f32_e32 v47, v47, v137
	v_lshlrev_b32_e32 v130, 16, v84
	v_and_b32_e32 v131, 0xffff0000, v84
	v_lshlrev_b32_e32 v132, 16, v85
	v_and_b32_e32 v133, 0xffff0000, v85
	v_lshlrev_b32_e32 v134, 16, v86
	v_and_b32_e32 v135, 0xffff0000, v86
	v_lshlrev_b32_e32 v136, 16, v87
	v_and_b32_e32 v137, 0xffff0000, v87
	v_add_f32_e32 v40, v40, v130
	v_add_f32_e32 v44, v44, v131
	v_add_f32_e32 v41, v41, v132
	v_add_f32_e32 v45, v45, v133
	v_add_f32_e32 v42, v42, v134
	v_add_f32_e32 v46, v46, v135
	v_add_f32_e32 v43, v43, v136
	v_add_f32_e32 v47, v47, v137
	v_lshlrev_b32_e32 v130, 16, v88
	v_and_b32_e32 v131, 0xffff0000, v88
	v_lshlrev_b32_e32 v132, 16, v89
	v_and_b32_e32 v133, 0xffff0000, v89
	v_lshlrev_b32_e32 v134, 16, v90
	v_and_b32_e32 v135, 0xffff0000, v90
	v_lshlrev_b32_e32 v136, 16, v91
	v_and_b32_e32 v137, 0xffff0000, v91
	v_add_f32_e32 v40, v40, v130
	v_add_f32_e32 v44, v44, v131
	v_add_f32_e32 v41, v41, v132
	v_add_f32_e32 v45, v45, v133
	v_add_f32_e32 v42, v42, v134
	v_add_f32_e32 v46, v46, v135
	v_add_f32_e32 v43, v43, v136
	v_add_f32_e32 v47, v47, v137
	s_andn2_b64 exec, exec, s[4:5]
	v_lshlrev_b32_e32 v130, 16, v92
	v_and_b32_e32 v131, 0xffff0000, v92
	v_lshlrev_b32_e32 v132, 16, v93
	v_and_b32_e32 v133, 0xffff0000, v93
	v_lshlrev_b32_e32 v134, 16, v94
	v_and_b32_e32 v135, 0xffff0000, v94
	v_lshlrev_b32_e32 v136, 16, v95
	v_and_b32_e32 v137, 0xffff0000, v95
	v_add_f32_e32 v40, v40, v130
	v_add_f32_e32 v44, v44, v131
	v_add_f32_e32 v41, v41, v132
	v_add_f32_e32 v45, v45, v133
	v_add_f32_e32 v42, v42, v134
	v_add_f32_e32 v46, v46, v135
	v_add_f32_e32 v43, v43, v136
	v_add_f32_e32 v47, v47, v137
	v_lshlrev_b32_e32 v130, 16, v96
	v_and_b32_e32 v131, 0xffff0000, v96
	v_lshlrev_b32_e32 v132, 16, v97
	v_and_b32_e32 v133, 0xffff0000, v97
	v_lshlrev_b32_e32 v134, 16, v98
	v_and_b32_e32 v135, 0xffff0000, v98
	v_lshlrev_b32_e32 v136, 16, v99
	v_and_b32_e32 v137, 0xffff0000, v99
	v_add_f32_e32 v40, v40, v130
	v_add_f32_e32 v44, v44, v131
	v_add_f32_e32 v41, v41, v132
	v_add_f32_e32 v45, v45, v133
	v_add_f32_e32 v42, v42, v134
	v_add_f32_e32 v46, v46, v135
	v_add_f32_e32 v43, v43, v136
	v_add_f32_e32 v47, v47, v137
	v_lshlrev_b32_e32 v130, 16, v100
	v_and_b32_e32 v131, 0xffff0000, v100
	v_lshlrev_b32_e32 v132, 16, v101
	v_and_b32_e32 v133, 0xffff0000, v101
	v_lshlrev_b32_e32 v134, 16, v102
	v_and_b32_e32 v135, 0xffff0000, v102
	v_lshlrev_b32_e32 v136, 16, v103
	v_and_b32_e32 v137, 0xffff0000, v103
	v_add_f32_e32 v40, v40, v130
	v_add_f32_e32 v44, v44, v131
	v_add_f32_e32 v41, v41, v132
	v_add_f32_e32 v45, v45, v133
	v_add_f32_e32 v42, v42, v134
	v_add_f32_e32 v46, v46, v135
	v_add_f32_e32 v43, v43, v136
	v_add_f32_e32 v47, v47, v137
	v_lshlrev_b32_e32 v130, 16, v104
	v_and_b32_e32 v131, 0xffff0000, v104
	v_lshlrev_b32_e32 v132, 16, v105
	v_and_b32_e32 v133, 0xffff0000, v105
	v_lshlrev_b32_e32 v134, 16, v106
	v_and_b32_e32 v135, 0xffff0000, v106
	v_lshlrev_b32_e32 v136, 16, v107
	v_and_b32_e32 v137, 0xffff0000, v107
	v_add_f32_e32 v40, v40, v130
	v_add_f32_e32 v44, v44, v131
	v_add_f32_e32 v41, v41, v132
	v_add_f32_e32 v45, v45, v133
	v_add_f32_e32 v42, v42, v134
	v_add_f32_e32 v46, v46, v135
	v_add_f32_e32 v43, v43, v136
	v_add_f32_e32 v47, v47, v137
	v_lshlrev_b32_e32 v130, 16, v108
	v_and_b32_e32 v131, 0xffff0000, v108
	v_lshlrev_b32_e32 v132, 16, v109
	v_and_b32_e32 v133, 0xffff0000, v109
	v_lshlrev_b32_e32 v134, 16, v110
	v_and_b32_e32 v135, 0xffff0000, v110
	v_lshlrev_b32_e32 v136, 16, v111
	v_and_b32_e32 v137, 0xffff0000, v111
	v_add_f32_e32 v40, v40, v130
	v_add_f32_e32 v44, v44, v131
	v_add_f32_e32 v41, v41, v132
	v_add_f32_e32 v45, v45, v133
	v_add_f32_e32 v42, v42, v134
	v_add_f32_e32 v46, v46, v135
	v_add_f32_e32 v43, v43, v136
	v_add_f32_e32 v47, v47, v137
	v_lshlrev_b32_e32 v130, 16, v112
	v_and_b32_e32 v131, 0xffff0000, v112
	v_lshlrev_b32_e32 v132, 16, v113
	v_and_b32_e32 v133, 0xffff0000, v113
	v_lshlrev_b32_e32 v134, 16, v114
	v_and_b32_e32 v135, 0xffff0000, v114
	v_lshlrev_b32_e32 v136, 16, v115
	v_and_b32_e32 v137, 0xffff0000, v115
	v_add_f32_e32 v40, v40, v130
	v_add_f32_e32 v44, v44, v131
	v_add_f32_e32 v41, v41, v132
	v_add_f32_e32 v45, v45, v133
	v_add_f32_e32 v42, v42, v134
	v_add_f32_e32 v46, v46, v135
	v_add_f32_e32 v43, v43, v136
	v_add_f32_e32 v47, v47, v137
	v_lshlrev_b32_e32 v130, 16, v116
	v_and_b32_e32 v131, 0xffff0000, v116
	v_lshlrev_b32_e32 v132, 16, v117
	v_and_b32_e32 v133, 0xffff0000, v117
	v_lshlrev_b32_e32 v134, 16, v118
	v_and_b32_e32 v135, 0xffff0000, v118
	v_lshlrev_b32_e32 v136, 16, v119
	v_and_b32_e32 v137, 0xffff0000, v119
	v_add_f32_e32 v40, v40, v130
	v_add_f32_e32 v44, v44, v131
	v_add_f32_e32 v41, v41, v132
	v_add_f32_e32 v45, v45, v133
	v_add_f32_e32 v42, v42, v134
	v_add_f32_e32 v46, v46, v135
	v_add_f32_e32 v43, v43, v136
	v_add_f32_e32 v47, v47, v137
	v_lshlrev_b32_e32 v130, 16, v120
	v_and_b32_e32 v131, 0xffff0000, v120
	v_lshlrev_b32_e32 v132, 16, v121
	v_and_b32_e32 v133, 0xffff0000, v121
	v_lshlrev_b32_e32 v134, 16, v122
	v_and_b32_e32 v135, 0xffff0000, v122
	v_lshlrev_b32_e32 v136, 16, v123
	v_and_b32_e32 v137, 0xffff0000, v123
	v_add_f32_e32 v40, v40, v130
	v_add_f32_e32 v44, v44, v131
	v_add_f32_e32 v41, v41, v132
	v_add_f32_e32 v45, v45, v133
	v_add_f32_e32 v42, v42, v134
	v_add_f32_e32 v46, v46, v135
	v_add_f32_e32 v43, v43, v136
	v_add_f32_e32 v47, v47, v137
	s_mov_b64 exec, -1
	s_branch .LBB0_356
.Lpool_zero:
	v_mov_b32_e32 v40, 0
	v_mov_b32_e32 v44, 0
	v_mov_b32_e32 v41, 0
	v_mov_b32_e32 v45, 0
	v_mov_b32_e32 v42, 0
	v_mov_b32_e32 v46, 0
	v_mov_b32_e32 v43, 0
	v_mov_b32_e32 v47, 0

.LBB0_364:
	s_or_b64 exec, exec, s[10:11]
	global_load_dwordx4 v[8:11], v[48:49], off
	s_add_i32 s19, s18, 7
	v_cmp_ge_i32_e32 vcc, s19, v53
	v_mov_b32_e32 v1, 0
	v_mov_b32_e32 v2, 0
	v_mov_b32_e32 v3, 0
	s_and_saveexec_b64 s[10:11], vcc
	s_cbranch_execz .LBB0_357
	global_load_dwordx4 v[0:3], v[50:51], off offset:1024
	s_branch .LBB0_357
.LBB0_379:
	v_readfirstlane_b32 s5, v209
	s_movk_i32 s0, 0x100
	s_cmpk_gt_i32 s2, 0x5ff
	s_cbranch_scc1 .LBB0_404
	v_lshrrev_b32_e32 v0, 5, v209
	v_lshrrev_b32_e32 v2, 1, v209
	v_and_b32_e32 v0, 4, v0
	v_bfe_u32 v1, v209, 2, 2
	v_and_b32_e32 v2, 24, v2
	v_or3_b32 v0, v0, v1, v2
	v_lshlrev_b32_e32 v1, 4, v209
	v_add_u32_e32 v2, 0x2000, v1
	v_lshrrev_b32_e32 v2, 7, v2
	v_and_b32_e32 v4, 32, v209
	s_movk_i32 s4, 0xe0
	v_bitop3_b32 v12, v1, v4, 48 bitop3:0x6c
	v_and_b32_e32 v13, 64, v209
	v_and_b32_e32 v14, 0xf0, v2
	v_bfe_u32 v15, v209, 2, 4
	v_and_or_b32 v3, v2, s4, v0
	v_or_b32_e32 v1, v12, v13
	v_or_b32_e32 v2, v14, v15
	v_lshrrev_b32_e32 v1, 1, v1
	v_mul_lo_u32 v2, s0, v2
	v_add_lshl_u32 v146, v2, v1, 1
	v_lshrrev_b32_e32 v2, 3, v209
	s_movk_i32 s4, 0x60
	s_ashr_i32 s27, s2, 31
	v_and_or_b32 v0, v2, s4, v0
	s_lshr_b32 s4, s27, 29
	s_add_i32 s4, s2, s4
	s_lshr_b32 s18, s5, 6
	s_ashr_i32 s1, s0, 31
	s_ashr_i32 s10, s4, 3
	s_and_b32 s4, s4, -8
	s_lshr_b32 s19, s5, 8
	s_lshl_b64 s[6:7], s[0:1], 8
	s_lshl_b64 s[48:49], s[0:1], 9
	s_lshl_b32 s26, s18, 10
	s_sub_i32 s4, s2, s4
	s_cmp_lt_i32 s4, 0
	s_movk_i32 s34, 0xc1
	s_cselect_b32 s11, s34, 0xc0
	s_mul_i32 s4, s4, s11
	s_add_i32 s4, s4, s10
	s_mul_hi_i32 s10, s4, 0x2aaaaaab
	s_lshr_b32 s11, s10, 31
	s_ashr_i32 s10, s10, 3
	s_add_i32 s10, s10, s11
	s_lshl_b32 s11, s10, 3
	s_mul_i32 s10, s10, 48
	s_sub_i32 s10, s4, s10
	s_bfe_i32 s4, s10, 0x80000
	s_bfe_u32 s4, s4, 0x3000c
	s_add_i32 s16, s10, s4
	s_bfe_i32 s4, s16, 0x80000
	s_and_b32 s16, s16, 0xf8
	s_sub_i32 s10, s10, s16
	s_sext_i32_i8 s10, s10
	s_add_i32 s50, s11, s10
	s_ashr_i32 s10, s50, 31
	s_mul_i32 s10, s48, s10
	s_mul_hi_u32 s11, s48, s50
	s_sext_i32_i16 s17, s4
	s_add_i32 s16, s11, s10
	s_lshr_b64 s[10:11], s[0:1], 23
	s_lshr_b32 s4, s17, 3
	s_mul_i32 s11, s10, s50
	s_add_i32 s16, s16, s11
	s_bfe_i64 s[52:53], s[4:5], 0x100000
	s_ashr_i32 s11, s17, 3
	s_mul_hi_u32 s17, s48, s11
	s_mul_i32 s35, s48, s53
	s_add_i32 s17, s17, s35
	s_mul_i32 s10, s10, s11
	s_add_i32 s17, s17, s10
	s_mul_i32 s10, s48, s11
	s_add_u32 s10, s74, s10
	v_mul_lo_u32 v0, s0, v0
	s_addc_u32 s11, s75, s17
	s_add_i32 s35, s26, 0
	v_add_lshl_u32 v148, v0, v1, 1
	s_add_i32 m0, s35, 0x10000
	v_mul_lo_u32 v3, s0, v3
	global_load_lds_dwordx4 v148, s[10:11]
	s_add_i32 m0, s35, 0x12000
	v_add_lshl_u32 v144, v3, v1, 1
	s_add_u32 s52, s10, s6
	global_load_lds_dwordx4 v144, s[10:11]
	s_addc_u32 s53, s11, s7
	s_add_i32 m0, s35, 0x14000
	v_and_b32_e32 v16, 0x70, v2
	s_mul_i32 s33, s48, s50
	global_load_lds_dwordx4 v148, s[52:53]
	s_add_i32 m0, s35, 0x16000
	v_or_b32_e32 v0, v16, v15
	s_add_u32 s84, s36, s33
	v_mul_lo_u32 v0, s0, v0
	s_addc_u32 s85, s37, s16
	s_add_i32 s62, s35, 0x2000
	v_add_lshl_u32 v150, v0, v1, 1
	global_load_lds_dwordx4 v144, s[52:53]
	s_mov_b32 m0, s35
	s_add_u32 s68, s84, s6
	global_load_lds_dwordx4 v150, s[84:85]
	s_mov_b32 m0, s62
	s_addc_u32 s69, s85, s7
	s_add_i32 s63, s35, 0x4000
	global_load_lds_dwordx4 v146, s[84:85]
	s_mov_b32 m0, s63
	s_add_i32 s64, s35, 0x6000
	global_load_lds_dwordx4 v150, s[68:69]
	s_mov_b32 m0, s64
	v_writelane_b32 v244, s94, 33
	global_load_lds_dwordx4 v146, s[68:69]
	v_mov_b32_e32 v153, 0
	v_writelane_b32 v244, s95, 34
	v_mov_b32_e32 v149, v153
	v_mov_b32_e32 v145, v153
	v_mov_b32_e32 v151, v153
	v_mov_b32_e32 v147, v153
	s_cmp_eq_u32 s19, 1
	s_mov_b64 s[8:9], s[90:91]
	v_writelane_b32 v244, s97, 31
	s_mov_b32 s51, 0
	v_lshl_add_u64 v[8:9], s[10:11], 0, v[148:149]
	v_lshl_add_u64 v[4:5], s[10:11], 0, v[144:145]
	v_lshl_add_u64 v[2:3], s[52:53], 0, v[148:149]
	v_lshl_add_u64 v[0:1], s[52:53], 0, v[144:145]
	v_lshl_add_u64 v[6:7], s[84:85], 0, v[150:151]
	s_cselect_b64 s[52:53], -1, 0
	s_cmp_lg_u32 s19, 1
	v_lshl_add_u64 v[10:11], s[84:85], 0, v[146:147]
	v_writelane_b32 v244, s96, 32
	s_cbranch_scc1 .LBB0_382
	s_barrier

.LBB0_404:
	v_readlane_b32 s0, v244, 17
	s_cmpk_gt_i32 s0, 0x3fff
	v_readlane_b32 s1, v244, 18
	s_cbranch_scc1 .LBB0_407
	v_readlane_b32 s1, v244, 16
	s_lshl_b32 s0, s3, 5
	s_lshl_b32 s1, s1, 2
	v_lshlrev_b32_e32 v0, 4, v209
	s_add_i32 s1, s1, s0
	v_readlane_b32 s4, v244, 27
	v_and_b32_e32 v2, 0xf0, v0
	v_mov_b32_e32 v3, 0
	v_or_b32_e32 v4, s1, v155
	v_readlane_b32 s5, v244, 28
	v_readlane_b32 s6, v244, 29
	v_readlane_b32 s7, v244, 30
	v_readlane_b32 s0, v244, 17
	v_lshl_add_u64 v[0:1], s[22:23], 0, v[2:3]
	v_lshl_add_u64 v[2:3], s[44:45], 0, v[2:3]
	s_lshl_b32 s4, s6, 5
	v_mov_b32_e32 v6, 0x358637bd
	s_mov_b32 s5, 0xf800000
	v_mov_b32_e32 v7, 0x260
	s_mov_b32 s6, 0xffff0000
	s_movk_i32 s7, 0x7fff
	s_mov_b32 s10, s0
	v_readlane_b32 s1, v244, 18
	v_ashrrev_i32_e32 v5, 31, v4
	v_lshl_add_u64 v[8:9], v[4:5], 2, s[70:71]
	global_load_dword v50, v[8:9], off
	v_lshlrev_b64 v[12:13], 8, v[4:5]
	v_lshl_add_u64 v[8:9], v[0:1], 0, v[12:13]
	global_load_dwordx4 v[64:67], v[8:9], off
	v_lshl_add_u64 v[100:101], v[2:3], 0, v[12:13]
	v_add_u32_e32 v4, s4, v4
	v_ashrrev_i32_e32 v5, 31, v4
	v_lshl_add_u64 v[8:9], v[4:5], 2, s[70:71]
	global_load_dword v51, v[8:9], off
	v_lshlrev_b64 v[12:13], 8, v[4:5]
	v_lshl_add_u64 v[8:9], v[0:1], 0, v[12:13]
	global_load_dwordx4 v[68:71], v[8:9], off
	v_lshl_add_u64 v[102:103], v[2:3], 0, v[12:13]
	v_add_u32_e32 v4, s4, v4
	v_ashrrev_i32_e32 v5, 31, v4
	v_lshl_add_u64 v[8:9], v[4:5], 2, s[70:71]
	global_load_dword v52, v[8:9], off
	v_lshlrev_b64 v[12:13], 8, v[4:5]
	v_lshl_add_u64 v[8:9], v[0:1], 0, v[12:13]
	global_load_dwordx4 v[72:75], v[8:9], off
	v_lshl_add_u64 v[104:105], v[2:3], 0, v[12:13]
	v_add_u32_e32 v4, s4, v4
	v_ashrrev_i32_e32 v5, 31, v4
	v_lshl_add_u64 v[8:9], v[4:5], 2, s[70:71]
	global_load_dword v53, v[8:9], off
	v_lshlrev_b64 v[12:13], 8, v[4:5]
	v_lshl_add_u64 v[8:9], v[0:1], 0, v[12:13]
	global_load_dwordx4 v[76:79], v[8:9], off
	v_lshl_add_u64 v[106:107], v[2:3], 0, v[12:13]
	v_add_u32_e32 v4, s4, v4
	v_ashrrev_i32_e32 v5, 31, v4
	v_lshl_add_u64 v[8:9], v[4:5], 2, s[70:71]
	global_load_dword v54, v[8:9], off
	v_lshlrev_b64 v[12:13], 8, v[4:5]
	v_lshl_add_u64 v[8:9], v[0:1], 0, v[12:13]
	global_load_dwordx4 v[80:83], v[8:9], off
	v_lshl_add_u64 v[108:109], v[2:3], 0, v[12:13]
	v_add_u32_e32 v4, s4, v4
	v_ashrrev_i32_e32 v5, 31, v4
	v_lshl_add_u64 v[8:9], v[4:5], 2, s[70:71]
	global_load_dword v55, v[8:9], off
	v_lshlrev_b64 v[12:13], 8, v[4:5]
	v_lshl_add_u64 v[8:9], v[0:1], 0, v[12:13]
	global_load_dwordx4 v[84:87], v[8:9], off
	v_lshl_add_u64 v[110:111], v[2:3], 0, v[12:13]
	v_add_u32_e32 v4, s4, v4
	v_ashrrev_i32_e32 v5, 31, v4
	v_lshl_add_u64 v[8:9], v[4:5], 2, s[70:71]
	global_load_dword v56, v[8:9], off
	v_lshlrev_b64 v[12:13], 8, v[4:5]
	v_lshl_add_u64 v[8:9], v[0:1], 0, v[12:13]
	global_load_dwordx4 v[88:91], v[8:9], off
	v_lshl_add_u64 v[112:113], v[2:3], 0, v[12:13]
	v_add_u32_e32 v4, s4, v4
	v_ashrrev_i32_e32 v5, 31, v4
	v_lshl_add_u64 v[8:9], v[4:5], 2, s[70:71]
	global_load_dword v57, v[8:9], off
	v_lshlrev_b64 v[12:13], 8, v[4:5]
	v_lshl_add_u64 v[8:9], v[0:1], 0, v[12:13]
	global_load_dwordx4 v[92:95], v[8:9], off
	v_lshl_add_u64 v[114:115], v[2:3], 0, v[12:13]
	v_add_u32_e32 v4, s4, v4
	s_waitcnt vmcnt(14)
	v_mov_b32_e32 v14, v50
	v_mov_b32_e32 v8, v64
	v_mov_b32_e32 v9, v65
	v_mov_b32_e32 v10, v66
	v_mov_b32_e32 v11, v67
	v_fmamk_f32 v5, v14, 0x3c000000, v6
	v_mul_f32_e32 v16, 0x4f800000, v5
	v_cmp_gt_f32_e32 vcc, s5, v5
	v_lshlrev_b32_e32 v15, 16, v9
	v_lshlrev_b32_e32 v14, 16, v8
	v_cndmask_b32_e32 v5, v5, v16, vcc
	v_sqrt_f32_e32 v18, v5
	v_lshlrev_b32_e32 v17, 16, v11
	v_lshlrev_b32_e32 v16, 16, v10
	v_and_b32_e32 v11, 0xffff0000, v11
	v_add_u32_e32 v19, -1, v18
	v_add_u32_e32 v20, 1, v18
	v_fma_f32 v21, -v19, v18, v5
	v_fma_f32 v22, -v20, v18, v5
	v_cmp_ge_f32_e64 s[0:1], 0, v21
	v_and_b32_e32 v10, 0xffff0000, v10
	v_and_b32_e32 v9, 0xffff0000, v9
	v_cndmask_b32_e64 v18, v18, v19, s[0:1]
	v_cmp_lt_f32_e64 s[0:1], 0, v22
	v_and_b32_e32 v8, 0xffff0000, v8
	s_nop 0
	v_cndmask_b32_e64 v18, v18, v20, s[0:1]
	v_mul_f32_e32 v19, 0x37800000, v18
	v_cndmask_b32_e32 v18, v18, v19, vcc
	v_cmp_class_f32_e32 vcc, v5, v7
	s_nop 1
	v_cndmask_b32_e32 v5, v18, v5, vcc
	v_div_scale_f32 v18, s[0:1], v5, v5, 1.0
	v_rcp_f32_e32 v19, v18
	v_div_scale_f32 v20, vcc, 1.0, v5, 1.0
	v_fma_f32 v21, -v18, v19, 1.0
	v_fmac_f32_e32 v19, v21, v19
	v_mul_f32_e32 v21, v20, v19
	v_fma_f32 v22, -v18, v21, v20
	v_fmac_f32_e32 v21, v22, v19
	v_fma_f32 v18, -v18, v21, v20
	v_div_fmas_f32 v18, v18, v19, v21
	v_div_fixup_f32 v18, v18, v5, 1.0
	v_pk_mul_f32 v[14:15], v[18:19], v[14:15] op_sel_hi:[0,1]
	v_pk_mul_f32 v[16:17], v[18:19], v[16:17] op_sel_hi:[0,1]
	v_pk_mul_f32 v[10:11], v[18:19], v[10:11] op_sel_hi:[0,1]
	v_pk_mul_f32 v[8:9], v[18:19], v[8:9] op_sel_hi:[0,1]
	v_bfe_u32 v5, v11, 16, 1
	v_bfe_u32 v21, v14, 16, 1
	v_bfe_u32 v22, v15, 16, 1
	v_bfe_u32 v23, v16, 16, 1
	v_bfe_u32 v24, v17, 16, 1
	v_bfe_u32 v18, v10, 16, 1
	v_bfe_u32 v19, v9, 16, 1
	v_bfe_u32 v20, v8, 16, 1
	v_add3_u32 v5, v11, v5, s7
	v_add3_u32 v11, v17, v24, s7
	v_add3_u32 v16, v16, v23, s7
	v_add3_u32 v15, v15, v22, s7
	v_add3_u32 v14, v14, v21, s7
	v_add3_u32 v8, v8, v20, s7
	v_add3_u32 v9, v9, v19, s7
	v_add3_u32 v10, v10, v18, s7
	v_lshrrev_b32_e32 v14, 16, v14
	v_lshrrev_b32_e32 v15, 16, v15
	v_lshrrev_b32_e32 v16, 16, v16
	v_lshrrev_b32_e32 v11, 16, v11
	v_and_or_b32 v11, v5, s6, v11
	v_and_or_b32 v10, v10, s6, v16
	v_and_or_b32 v9, v9, s6, v15
	v_and_or_b32 v8, v8, s6, v14
	global_store_dwordx4 v[100:101], v[8:11], off
	s_nop 1
	s_waitcnt vmcnt(13)
	v_mov_b32_e32 v14, v51
	v_mov_b32_e32 v8, v68
	v_mov_b32_e32 v9, v69
	v_mov_b32_e32 v10, v70
	v_mov_b32_e32 v11, v71
	v_fmamk_f32 v5, v14, 0x3c000000, v6
	v_mul_f32_e32 v16, 0x4f800000, v5
	v_cmp_gt_f32_e32 vcc, s5, v5
	v_lshlrev_b32_e32 v15, 16, v9
	v_lshlrev_b32_e32 v14, 16, v8
	v_cndmask_b32_e32 v5, v5, v16, vcc
	v_sqrt_f32_e32 v18, v5
	v_lshlrev_b32_e32 v17, 16, v11
	v_lshlrev_b32_e32 v16, 16, v10
	v_and_b32_e32 v11, 0xffff0000, v11
	v_add_u32_e32 v19, -1, v18
	v_add_u32_e32 v20, 1, v18
	v_fma_f32 v21, -v19, v18, v5
	v_fma_f32 v22, -v20, v18, v5
	v_cmp_ge_f32_e64 s[0:1], 0, v21
	v_and_b32_e32 v10, 0xffff0000, v10
	v_and_b32_e32 v9, 0xffff0000, v9
	v_cndmask_b32_e64 v18, v18, v19, s[0:1]
	v_cmp_lt_f32_e64 s[0:1], 0, v22
	v_and_b32_e32 v8, 0xffff0000, v8
	s_nop 0
	v_cndmask_b32_e64 v18, v18, v20, s[0:1]
	v_mul_f32_e32 v19, 0x37800000, v18
	v_cndmask_b32_e32 v18, v18, v19, vcc
	v_cmp_class_f32_e32 vcc, v5, v7
	s_nop 1
	v_cndmask_b32_e32 v5, v18, v5, vcc
	v_div_scale_f32 v18, s[0:1], v5, v5, 1.0
	v_rcp_f32_e32 v19, v18
	v_div_scale_f32 v20, vcc, 1.0, v5, 1.0
	v_fma_f32 v21, -v18, v19, 1.0
	v_fmac_f32_e32 v19, v21, v19
	v_mul_f32_e32 v21, v20, v19
	v_fma_f32 v22, -v18, v21, v20
	v_fmac_f32_e32 v21, v22, v19
	v_fma_f32 v18, -v18, v21, v20
	v_div_fmas_f32 v18, v18, v19, v21
	v_div_fixup_f32 v18, v18, v5, 1.0
	v_pk_mul_f32 v[14:15], v[18:19], v[14:15] op_sel_hi:[0,1]
	v_pk_mul_f32 v[16:17], v[18:19], v[16:17] op_sel_hi:[0,1]
	v_pk_mul_f32 v[10:11], v[18:19], v[10:11] op_sel_hi:[0,1]
	v_pk_mul_f32 v[8:9], v[18:19], v[8:9] op_sel_hi:[0,1]
	v_bfe_u32 v5, v11, 16, 1
	v_bfe_u32 v21, v14, 16, 1
	v_bfe_u32 v22, v15, 16, 1
	v_bfe_u32 v23, v16, 16, 1
	v_bfe_u32 v24, v17, 16, 1
	v_bfe_u32 v18, v10, 16, 1
	v_bfe_u32 v19, v9, 16, 1
	v_bfe_u32 v20, v8, 16, 1
	v_add3_u32 v5, v11, v5, s7
	v_add3_u32 v11, v17, v24, s7
	v_add3_u32 v16, v16, v23, s7
	v_add3_u32 v15, v15, v22, s7
	v_add3_u32 v14, v14, v21, s7
	v_add3_u32 v8, v8, v20, s7
	v_add3_u32 v9, v9, v19, s7
	v_add3_u32 v10, v10, v18, s7
	v_lshrrev_b32_e32 v14, 16, v14
	v_lshrrev_b32_e32 v15, 16, v15
	v_lshrrev_b32_e32 v16, 16, v16
	v_lshrrev_b32_e32 v11, 16, v11
	v_and_or_b32 v11, v5, s6, v11
	v_and_or_b32 v10, v10, s6, v16
	v_and_or_b32 v9, v9, s6, v15
	v_and_or_b32 v8, v8, s6, v14
	global_store_dwordx4 v[102:103], v[8:11], off
	s_nop 1
	s_waitcnt vmcnt(12)
	v_mov_b32_e32 v14, v52
	v_mov_b32_e32 v8, v72
	v_mov_b32_e32 v9, v73
	v_mov_b32_e32 v10, v74
	v_mov_b32_e32 v11, v75
	v_fmamk_f32 v5, v14, 0x3c000000, v6
	v_mul_f32_e32 v16, 0x4f800000, v5
	v_cmp_gt_f32_e32 vcc, s5, v5
	v_lshlrev_b32_e32 v15, 16, v9
	v_lshlrev_b32_e32 v14, 16, v8
	v_cndmask_b32_e32 v5, v5, v16, vcc
	v_sqrt_f32_e32 v18, v5
	v_lshlrev_b32_e32 v17, 16, v11
	v_lshlrev_b32_e32 v16, 16, v10
	v_and_b32_e32 v11, 0xffff0000, v11
	v_add_u32_e32 v19, -1, v18
	v_add_u32_e32 v20, 1, v18
	v_fma_f32 v21, -v19, v18, v5
	v_fma_f32 v22, -v20, v18, v5
	v_cmp_ge_f32_e64 s[0:1], 0, v21
	v_and_b32_e32 v10, 0xffff0000, v10
	v_and_b32_e32 v9, 0xffff0000, v9
	v_cndmask_b32_e64 v18, v18, v19, s[0:1]
	v_cmp_lt_f32_e64 s[0:1], 0, v22
	v_and_b32_e32 v8, 0xffff0000, v8
	s_nop 0
	v_cndmask_b32_e64 v18, v18, v20, s[0:1]
	v_mul_f32_e32 v19, 0x37800000, v18
	v_cndmask_b32_e32 v18, v18, v19, vcc
	v_cmp_class_f32_e32 vcc, v5, v7
	s_nop 1
	v_cndmask_b32_e32 v5, v18, v5, vcc
	v_div_scale_f32 v18, s[0:1], v5, v5, 1.0
	v_rcp_f32_e32 v19, v18
	v_div_scale_f32 v20, vcc, 1.0, v5, 1.0
	v_fma_f32 v21, -v18, v19, 1.0
	v_fmac_f32_e32 v19, v21, v19
	v_mul_f32_e32 v21, v20, v19
	v_fma_f32 v22, -v18, v21, v20
	v_fmac_f32_e32 v21, v22, v19
	v_fma_f32 v18, -v18, v21, v20
	v_div_fmas_f32 v18, v18, v19, v21
	v_div_fixup_f32 v18, v18, v5, 1.0
	v_pk_mul_f32 v[14:15], v[18:19], v[14:15] op_sel_hi:[0,1]
	v_pk_mul_f32 v[16:17], v[18:19], v[16:17] op_sel_hi:[0,1]
	v_pk_mul_f32 v[10:11], v[18:19], v[10:11] op_sel_hi:[0,1]
	v_pk_mul_f32 v[8:9], v[18:19], v[8:9] op_sel_hi:[0,1]
	v_bfe_u32 v5, v11, 16, 1
	v_bfe_u32 v21, v14, 16, 1
	v_bfe_u32 v22, v15, 16, 1
	v_bfe_u32 v23, v16, 16, 1
	v_bfe_u32 v24, v17, 16, 1
	v_bfe_u32 v18, v10, 16, 1
	v_bfe_u32 v19, v9, 16, 1
	v_bfe_u32 v20, v8, 16, 1
	v_add3_u32 v5, v11, v5, s7
	v_add3_u32 v11, v17, v24, s7
	v_add3_u32 v16, v16, v23, s7
	v_add3_u32 v15, v15, v22, s7
	v_add3_u32 v14, v14, v21, s7
	v_add3_u32 v8, v8, v20, s7
	v_add3_u32 v9, v9, v19, s7
	v_add3_u32 v10, v10, v18, s7
	v_lshrrev_b32_e32 v14, 16, v14
	v_lshrrev_b32_e32 v15, 16, v15
	v_lshrrev_b32_e32 v16, 16, v16
	v_lshrrev_b32_e32 v11, 16, v11
	v_and_or_b32 v11, v5, s6, v11
	v_and_or_b32 v10, v10, s6, v16
	v_and_or_b32 v9, v9, s6, v15
	v_and_or_b32 v8, v8, s6, v14
	global_store_dwordx4 v[104:105], v[8:11], off
	s_nop 1
	s_waitcnt vmcnt(11)
	v_mov_b32_e32 v14, v53
	v_mov_b32_e32 v8, v76
	v_mov_b32_e32 v9, v77
	v_mov_b32_e32 v10, v78
	v_mov_b32_e32 v11, v79
	v_fmamk_f32 v5, v14, 0x3c000000, v6
	v_mul_f32_e32 v16, 0x4f800000, v5
	v_cmp_gt_f32_e32 vcc, s5, v5
	v_lshlrev_b32_e32 v15, 16, v9
	v_lshlrev_b32_e32 v14, 16, v8
	v_cndmask_b32_e32 v5, v5, v16, vcc
	v_sqrt_f32_e32 v18, v5
	v_lshlrev_b32_e32 v17, 16, v11
	v_lshlrev_b32_e32 v16, 16, v10
	v_and_b32_e32 v11, 0xffff0000, v11
	v_add_u32_e32 v19, -1, v18
	v_add_u32_e32 v20, 1, v18
	v_fma_f32 v21, -v19, v18, v5
	v_fma_f32 v22, -v20, v18, v5
	v_cmp_ge_f32_e64 s[0:1], 0, v21
	v_and_b32_e32 v10, 0xffff0000, v10
	v_and_b32_e32 v9, 0xffff0000, v9
	v_cndmask_b32_e64 v18, v18, v19, s[0:1]
	v_cmp_lt_f32_e64 s[0:1], 0, v22
	v_and_b32_e32 v8, 0xffff0000, v8
	s_nop 0
	v_cndmask_b32_e64 v18, v18, v20, s[0:1]
	v_mul_f32_e32 v19, 0x37800000, v18
	v_cndmask_b32_e32 v18, v18, v19, vcc
	v_cmp_class_f32_e32 vcc, v5, v7
	s_nop 1
	v_cndmask_b32_e32 v5, v18, v5, vcc
	v_div_scale_f32 v18, s[0:1], v5, v5, 1.0
	v_rcp_f32_e32 v19, v18
	v_div_scale_f32 v20, vcc, 1.0, v5, 1.0
	v_fma_f32 v21, -v18, v19, 1.0
	v_fmac_f32_e32 v19, v21, v19
	v_mul_f32_e32 v21, v20, v19
	v_fma_f32 v22, -v18, v21, v20
	v_fmac_f32_e32 v21, v22, v19
	v_fma_f32 v18, -v18, v21, v20
	v_div_fmas_f32 v18, v18, v19, v21
	v_div_fixup_f32 v18, v18, v5, 1.0
	v_pk_mul_f32 v[14:15], v[18:19], v[14:15] op_sel_hi:[0,1]
	v_pk_mul_f32 v[16:17], v[18:19], v[16:17] op_sel_hi:[0,1]
	v_pk_mul_f32 v[10:11], v[18:19], v[10:11] op_sel_hi:[0,1]
	v_pk_mul_f32 v[8:9], v[18:19], v[8:9] op_sel_hi:[0,1]
	v_bfe_u32 v5, v11, 16, 1
	v_bfe_u32 v21, v14, 16, 1
	v_bfe_u32 v22, v15, 16, 1
	v_bfe_u32 v23, v16, 16, 1
	v_bfe_u32 v24, v17, 16, 1
	v_bfe_u32 v18, v10, 16, 1
	v_bfe_u32 v19, v9, 16, 1
	v_bfe_u32 v20, v8, 16, 1
	v_add3_u32 v5, v11, v5, s7
	v_add3_u32 v11, v17, v24, s7
	v_add3_u32 v16, v16, v23, s7
	v_add3_u32 v15, v15, v22, s7
	v_add3_u32 v14, v14, v21, s7
	v_add3_u32 v8, v8, v20, s7
	v_add3_u32 v9, v9, v19, s7
	v_add3_u32 v10, v10, v18, s7
	v_lshrrev_b32_e32 v14, 16, v14
	v_lshrrev_b32_e32 v15, 16, v15
	v_lshrrev_b32_e32 v16, 16, v16
	v_lshrrev_b32_e32 v11, 16, v11
	v_and_or_b32 v11, v5, s6, v11
	v_and_or_b32 v10, v10, s6, v16
	v_and_or_b32 v9, v9, s6, v15
	v_and_or_b32 v8, v8, s6, v14
	global_store_dwordx4 v[106:107], v[8:11], off
	s_nop 1
	s_waitcnt vmcnt(10)
	v_mov_b32_e32 v14, v54
	v_mov_b32_e32 v8, v80
	v_mov_b32_e32 v9, v81
	v_mov_b32_e32 v10, v82
	v_mov_b32_e32 v11, v83
	v_fmamk_f32 v5, v14, 0x3c000000, v6
	v_mul_f32_e32 v16, 0x4f800000, v5
	v_cmp_gt_f32_e32 vcc, s5, v5
	v_lshlrev_b32_e32 v15, 16, v9
	v_lshlrev_b32_e32 v14, 16, v8
	v_cndmask_b32_e32 v5, v5, v16, vcc
	v_sqrt_f32_e32 v18, v5
	v_lshlrev_b32_e32 v17, 16, v11
	v_lshlrev_b32_e32 v16, 16, v10
	v_and_b32_e32 v11, 0xffff0000, v11
	v_add_u32_e32 v19, -1, v18
	v_add_u32_e32 v20, 1, v18
	v_fma_f32 v21, -v19, v18, v5
	v_fma_f32 v22, -v20, v18, v5
	v_cmp_ge_f32_e64 s[0:1], 0, v21
	v_and_b32_e32 v10, 0xffff0000, v10
	v_and_b32_e32 v9, 0xffff0000, v9
	v_cndmask_b32_e64 v18, v18, v19, s[0:1]
	v_cmp_lt_f32_e64 s[0:1], 0, v22
	v_and_b32_e32 v8, 0xffff0000, v8
	s_nop 0
	v_cndmask_b32_e64 v18, v18, v20, s[0:1]
	v_mul_f32_e32 v19, 0x37800000, v18
	v_cndmask_b32_e32 v18, v18, v19, vcc
	v_cmp_class_f32_e32 vcc, v5, v7
	s_nop 1
	v_cndmask_b32_e32 v5, v18, v5, vcc
	v_div_scale_f32 v18, s[0:1], v5, v5, 1.0
	v_rcp_f32_e32 v19, v18
	v_div_scale_f32 v20, vcc, 1.0, v5, 1.0
	v_fma_f32 v21, -v18, v19, 1.0
	v_fmac_f32_e32 v19, v21, v19
	v_mul_f32_e32 v21, v20, v19
	v_fma_f32 v22, -v18, v21, v20
	v_fmac_f32_e32 v21, v22, v19
	v_fma_f32 v18, -v18, v21, v20
	v_div_fmas_f32 v18, v18, v19, v21
	v_div_fixup_f32 v18, v18, v5, 1.0
	v_pk_mul_f32 v[14:15], v[18:19], v[14:15] op_sel_hi:[0,1]
	v_pk_mul_f32 v[16:17], v[18:19], v[16:17] op_sel_hi:[0,1]
	v_pk_mul_f32 v[10:11], v[18:19], v[10:11] op_sel_hi:[0,1]
	v_pk_mul_f32 v[8:9], v[18:19], v[8:9] op_sel_hi:[0,1]
	v_bfe_u32 v5, v11, 16, 1
	v_bfe_u32 v21, v14, 16, 1
	v_bfe_u32 v22, v15, 16, 1
	v_bfe_u32 v23, v16, 16, 1
	v_bfe_u32 v24, v17, 16, 1
	v_bfe_u32 v18, v10, 16, 1
	v_bfe_u32 v19, v9, 16, 1
	v_bfe_u32 v20, v8, 16, 1
	v_add3_u32 v5, v11, v5, s7
	v_add3_u32 v11, v17, v24, s7
	v_add3_u32 v16, v16, v23, s7
	v_add3_u32 v15, v15, v22, s7
	v_add3_u32 v14, v14, v21, s7
	v_add3_u32 v8, v8, v20, s7
	v_add3_u32 v9, v9, v19, s7
	v_add3_u32 v10, v10, v18, s7
	v_lshrrev_b32_e32 v14, 16, v14
	v_lshrrev_b32_e32 v15, 16, v15
	v_lshrrev_b32_e32 v16, 16, v16
	v_lshrrev_b32_e32 v11, 16, v11
	v_and_or_b32 v11, v5, s6, v11
	v_and_or_b32 v10, v10, s6, v16
	v_and_or_b32 v9, v9, s6, v15
	v_and_or_b32 v8, v8, s6, v14
	global_store_dwordx4 v[108:109], v[8:11], off
	s_nop 1
	s_waitcnt vmcnt(9)
	v_mov_b32_e32 v14, v55
	v_mov_b32_e32 v8, v84
	v_mov_b32_e32 v9, v85
	v_mov_b32_e32 v10, v86
	v_mov_b32_e32 v11, v87
	v_fmamk_f32 v5, v14, 0x3c000000, v6
	v_mul_f32_e32 v16, 0x4f800000, v5
	v_cmp_gt_f32_e32 vcc, s5, v5
	v_lshlrev_b32_e32 v15, 16, v9
	v_lshlrev_b32_e32 v14, 16, v8
	v_cndmask_b32_e32 v5, v5, v16, vcc
	v_sqrt_f32_e32 v18, v5
	v_lshlrev_b32_e32 v17, 16, v11
	v_lshlrev_b32_e32 v16, 16, v10
	v_and_b32_e32 v11, 0xffff0000, v11
	v_add_u32_e32 v19, -1, v18
	v_add_u32_e32 v20, 1, v18
	v_fma_f32 v21, -v19, v18, v5
	v_fma_f32 v22, -v20, v18, v5
	v_cmp_ge_f32_e64 s[0:1], 0, v21
	v_and_b32_e32 v10, 0xffff0000, v10
	v_and_b32_e32 v9, 0xffff0000, v9
	v_cndmask_b32_e64 v18, v18, v19, s[0:1]
	v_cmp_lt_f32_e64 s[0:1], 0, v22
	v_and_b32_e32 v8, 0xffff0000, v8
	s_nop 0
	v_cndmask_b32_e64 v18, v18, v20, s[0:1]
	v_mul_f32_e32 v19, 0x37800000, v18
	v_cndmask_b32_e32 v18, v18, v19, vcc
	v_cmp_class_f32_e32 vcc, v5, v7
	s_nop 1
	v_cndmask_b32_e32 v5, v18, v5, vcc
	v_div_scale_f32 v18, s[0:1], v5, v5, 1.0
	v_rcp_f32_e32 v19, v18
	v_div_scale_f32 v20, vcc, 1.0, v5, 1.0
	v_fma_f32 v21, -v18, v19, 1.0
	v_fmac_f32_e32 v19, v21, v19
	v_mul_f32_e32 v21, v20, v19
	v_fma_f32 v22, -v18, v21, v20
	v_fmac_f32_e32 v21, v22, v19
	v_fma_f32 v18, -v18, v21, v20
	v_div_fmas_f32 v18, v18, v19, v21
	v_div_fixup_f32 v18, v18, v5, 1.0
	v_pk_mul_f32 v[14:15], v[18:19], v[14:15] op_sel_hi:[0,1]
	v_pk_mul_f32 v[16:17], v[18:19], v[16:17] op_sel_hi:[0,1]
	v_pk_mul_f32 v[10:11], v[18:19], v[10:11] op_sel_hi:[0,1]
	v_pk_mul_f32 v[8:9], v[18:19], v[8:9] op_sel_hi:[0,1]
	v_bfe_u32 v5, v11, 16, 1
	v_bfe_u32 v21, v14, 16, 1
	v_bfe_u32 v22, v15, 16, 1
	v_bfe_u32 v23, v16, 16, 1
	v_bfe_u32 v24, v17, 16, 1
	v_bfe_u32 v18, v10, 16, 1
	v_bfe_u32 v19, v9, 16, 1
	v_bfe_u32 v20, v8, 16, 1
	v_add3_u32 v5, v11, v5, s7
	v_add3_u32 v11, v17, v24, s7
	v_add3_u32 v16, v16, v23, s7
	v_add3_u32 v15, v15, v22, s7
	v_add3_u32 v14, v14, v21, s7
	v_add3_u32 v8, v8, v20, s7
	v_add3_u32 v9, v9, v19, s7
	v_add3_u32 v10, v10, v18, s7
	v_lshrrev_b32_e32 v14, 16, v14
	v_lshrrev_b32_e32 v15, 16, v15
	v_lshrrev_b32_e32 v16, 16, v16
	v_lshrrev_b32_e32 v11, 16, v11
	v_and_or_b32 v11, v5, s6, v11
	v_and_or_b32 v10, v10, s6, v16
	v_and_or_b32 v9, v9, s6, v15
	v_and_or_b32 v8, v8, s6, v14
	global_store_dwordx4 v[110:111], v[8:11], off
	s_nop 1
	s_waitcnt vmcnt(8)
	v_mov_b32_e32 v14, v56
	v_mov_b32_e32 v8, v88
	v_mov_b32_e32 v9, v89
	v_mov_b32_e32 v10, v90
	v_mov_b32_e32 v11, v91
	v_fmamk_f32 v5, v14, 0x3c000000, v6
	v_mul_f32_e32 v16, 0x4f800000, v5
	v_cmp_gt_f32_e32 vcc, s5, v5
	v_lshlrev_b32_e32 v15, 16, v9
	v_lshlrev_b32_e32 v14, 16, v8
	v_cndmask_b32_e32 v5, v5, v16, vcc
	v_sqrt_f32_e32 v18, v5
	v_lshlrev_b32_e32 v17, 16, v11
	v_lshlrev_b32_e32 v16, 16, v10
	v_and_b32_e32 v11, 0xffff0000, v11
	v_add_u32_e32 v19, -1, v18
	v_add_u32_e32 v20, 1, v18
	v_fma_f32 v21, -v19, v18, v5
	v_fma_f32 v22, -v20, v18, v5
	v_cmp_ge_f32_e64 s[0:1], 0, v21
	v_and_b32_e32 v10, 0xffff0000, v10
	v_and_b32_e32 v9, 0xffff0000, v9
	v_cndmask_b32_e64 v18, v18, v19, s[0:1]
	v_cmp_lt_f32_e64 s[0:1], 0, v22
	v_and_b32_e32 v8, 0xffff0000, v8
	s_nop 0
	v_cndmask_b32_e64 v18, v18, v20, s[0:1]
	v_mul_f32_e32 v19, 0x37800000, v18
	v_cndmask_b32_e32 v18, v18, v19, vcc
	v_cmp_class_f32_e32 vcc, v5, v7
	s_nop 1
	v_cndmask_b32_e32 v5, v18, v5, vcc
	v_div_scale_f32 v18, s[0:1], v5, v5, 1.0
	v_rcp_f32_e32 v19, v18
	v_div_scale_f32 v20, vcc, 1.0, v5, 1.0
	v_fma_f32 v21, -v18, v19, 1.0
	v_fmac_f32_e32 v19, v21, v19
	v_mul_f32_e32 v21, v20, v19
	v_fma_f32 v22, -v18, v21, v20
	v_fmac_f32_e32 v21, v22, v19
	v_fma_f32 v18, -v18, v21, v20
	v_div_fmas_f32 v18, v18, v19, v21
	v_div_fixup_f32 v18, v18, v5, 1.0
	v_pk_mul_f32 v[14:15], v[18:19], v[14:15] op_sel_hi:[0,1]
	v_pk_mul_f32 v[16:17], v[18:19], v[16:17] op_sel_hi:[0,1]
	v_pk_mul_f32 v[10:11], v[18:19], v[10:11] op_sel_hi:[0,1]
	v_pk_mul_f32 v[8:9], v[18:19], v[8:9] op_sel_hi:[0,1]
	v_bfe_u32 v5, v11, 16, 1
	v_bfe_u32 v21, v14, 16, 1
	v_bfe_u32 v22, v15, 16, 1
	v_bfe_u32 v23, v16, 16, 1
	v_bfe_u32 v24, v17, 16, 1
	v_bfe_u32 v18, v10, 16, 1
	v_bfe_u32 v19, v9, 16, 1
	v_bfe_u32 v20, v8, 16, 1
	v_add3_u32 v5, v11, v5, s7
	v_add3_u32 v11, v17, v24, s7
	v_add3_u32 v16, v16, v23, s7
	v_add3_u32 v15, v15, v22, s7
	v_add3_u32 v14, v14, v21, s7
	v_add3_u32 v8, v8, v20, s7
	v_add3_u32 v9, v9, v19, s7
	v_add3_u32 v10, v10, v18, s7
	v_lshrrev_b32_e32 v14, 16, v14
	v_lshrrev_b32_e32 v15, 16, v15
	v_lshrrev_b32_e32 v16, 16, v16
	v_lshrrev_b32_e32 v11, 16, v11
	v_and_or_b32 v11, v5, s6, v11
	v_and_or_b32 v10, v10, s6, v16
	v_and_or_b32 v9, v9, s6, v15
	v_and_or_b32 v8, v8, s6, v14
	global_store_dwordx4 v[112:113], v[8:11], off
	s_nop 1
	s_waitcnt vmcnt(7)
	v_mov_b32_e32 v14, v57
	v_mov_b32_e32 v8, v92
	v_mov_b32_e32 v9, v93
	v_mov_b32_e32 v10, v94
	v_mov_b32_e32 v11, v95
	v_fmamk_f32 v5, v14, 0x3c000000, v6
	v_mul_f32_e32 v16, 0x4f800000, v5
	v_cmp_gt_f32_e32 vcc, s5, v5
	v_lshlrev_b32_e32 v15, 16, v9
	v_lshlrev_b32_e32 v14, 16, v8
	v_cndmask_b32_e32 v5, v5, v16, vcc
	v_sqrt_f32_e32 v18, v5
	v_lshlrev_b32_e32 v17, 16, v11
	v_lshlrev_b32_e32 v16, 16, v10
	v_and_b32_e32 v11, 0xffff0000, v11
	v_add_u32_e32 v19, -1, v18
	v_add_u32_e32 v20, 1, v18
	v_fma_f32 v21, -v19, v18, v5
	v_fma_f32 v22, -v20, v18, v5
	v_cmp_ge_f32_e64 s[0:1], 0, v21
	v_and_b32_e32 v10, 0xffff0000, v10
	v_and_b32_e32 v9, 0xffff0000, v9
	v_cndmask_b32_e64 v18, v18, v19, s[0:1]
	v_cmp_lt_f32_e64 s[0:1], 0, v22
	v_and_b32_e32 v8, 0xffff0000, v8
	s_nop 0
	v_cndmask_b32_e64 v18, v18, v20, s[0:1]
	v_mul_f32_e32 v19, 0x37800000, v18
	v_cndmask_b32_e32 v18, v18, v19, vcc
	v_cmp_class_f32_e32 vcc, v5, v7
	s_nop 1
	v_cndmask_b32_e32 v5, v18, v5, vcc
	v_div_scale_f32 v18, s[0:1], v5, v5, 1.0
	v_rcp_f32_e32 v19, v18
	v_div_scale_f32 v20, vcc, 1.0, v5, 1.0
	v_fma_f32 v21, -v18, v19, 1.0
	v_fmac_f32_e32 v19, v21, v19
	v_mul_f32_e32 v21, v20, v19
	v_fma_f32 v22, -v18, v21, v20
	v_fmac_f32_e32 v21, v22, v19
	v_fma_f32 v18, -v18, v21, v20
	v_div_fmas_f32 v18, v18, v19, v21
	v_div_fixup_f32 v18, v18, v5, 1.0
	v_pk_mul_f32 v[14:15], v[18:19], v[14:15] op_sel_hi:[0,1]
	v_pk_mul_f32 v[16:17], v[18:19], v[16:17] op_sel_hi:[0,1]
	v_pk_mul_f32 v[10:11], v[18:19], v[10:11] op_sel_hi:[0,1]
	v_pk_mul_f32 v[8:9], v[18:19], v[8:9] op_sel_hi:[0,1]
	v_bfe_u32 v5, v11, 16, 1
	v_bfe_u32 v21, v14, 16, 1
	v_bfe_u32 v22, v15, 16, 1
	v_bfe_u32 v23, v16, 16, 1
	v_bfe_u32 v24, v17, 16, 1
	v_bfe_u32 v18, v10, 16, 1
	v_bfe_u32 v19, v9, 16, 1
	v_bfe_u32 v20, v8, 16, 1
	v_add3_u32 v5, v11, v5, s7
	v_add3_u32 v11, v17, v24, s7
	v_add3_u32 v16, v16, v23, s7
	v_add3_u32 v15, v15, v22, s7
	v_add3_u32 v14, v14, v21, s7
	v_add3_u32 v8, v8, v20, s7
	v_add3_u32 v9, v9, v19, s7
	v_add3_u32 v10, v10, v18, s7
	v_lshrrev_b32_e32 v14, 16, v14
	v_lshrrev_b32_e32 v15, 16, v15
	v_lshrrev_b32_e32 v16, 16, v16
	v_lshrrev_b32_e32 v11, 16, v11
	v_and_or_b32 v11, v5, s6, v11
	v_and_or_b32 v10, v10, s6, v16
	v_and_or_b32 v9, v9, s6, v15
	v_and_or_b32 v8, v8, s6, v14
	global_store_dwordx4 v[114:115], v[8:11], off
	s_nop 1
